# S2 epilogue: second f32 residual batch prefetched group by group into registers freed by the first batch (vmcnt(4)/vmcnt(3)), on top of S5/S7 prefetch
# speedup vs baseline: 1.0018x; 1.0018x over previous
.LBB0_489:
	v_lshl_add_u32 v196, s40, 8, v205
	v_lshl_add_u32 v192, s41, 8, v207
	v_ashrrev_i32_e32 v193, 31, v192
	v_ashrrev_i32_e32 v197, 31, v196
	v_lshl_add_u64 v[194:195], v[192:193], 2, s[52:53]
	v_lshlrev_b64 v[128:129], 13, v[196:197]
	v_lshl_add_u64 v[128:129], v[194:195], 0, v[128:129]
	global_load_dwordx4 v[214:217], v[128:129], off
	global_load_dwordx4 v[218:221], v[128:129], off offset:16
	global_load_dwordx4 v[222:225], v[128:129], off offset:512
	global_load_dwordx4 v[226:229], v[128:129], off offset:528
	v_or_b32_e32 v202, 16, v196
	v_or_b32_e32 v200, 32, v196
	v_or_b32_e32 v198, 48, v196
	v_ashrrev_i32_e32 v203, 31, v202
	v_ashrrev_i32_e32 v201, 31, v200
	v_ashrrev_i32_e32 v199, 31, v198
	v_lshlrev_b64 v[128:129], 13, v[202:203]
	v_lshlrev_b64 v[130:131], 13, v[200:201]
	v_lshlrev_b64 v[132:133], 13, v[198:199]
	v_lshl_add_u64 v[128:129], v[194:195], 0, v[128:129]
	v_lshl_add_u64 v[130:131], v[194:195], 0, v[130:131]
	v_lshl_add_u64 v[132:133], v[194:195], 0, v[132:133]
	global_load_dwordx4 v[168:171], v[128:129], off offset:16
	global_load_dwordx4 v[172:175], v[128:129], off
	global_load_dwordx4 v[160:163], v[128:129], off offset:528
	global_load_dwordx4 v[164:167], v[128:129], off offset:512
	global_load_dwordx4 v[152:155], v[130:131], off offset:16
	global_load_dwordx4 v[156:159], v[130:131], off
	global_load_dwordx4 v[144:147], v[130:131], off offset:528
	global_load_dwordx4 v[148:151], v[130:131], off offset:512
	global_load_dwordx4 v[136:139], v[132:133], off offset:16
	global_load_dwordx4 v[140:143], v[132:133], off
	s_nop 0
	global_load_dwordx4 v[128:131], v[132:133], off offset:528
	s_nop 0
	global_load_dwordx4 v[132:135], v[132:133], off offset:512
	v_add_u32_e32 v250, 0x80, v196
	v_ashrrev_i32_e32 v251, 31, v250
	v_lshlrev_b64 v[250:251], 13, v[250:251]
	v_lshl_add_u64 v[250:251], v[194:195], 0, v[250:251]
	global_load_dwordx4 v[234:237], v[250:251], off
	global_load_dwordx4 v[238:241], v[250:251], off offset:16
	global_load_dwordx4 v[242:245], v[250:251], off offset:512
	global_load_dwordx4 v[246:249], v[250:251], off offset:528
	v_and_b32_e32 v212, 64, v211
	v_xor_b32_e32 v204, 16, v211
	v_add_u32_e32 v231, 64, v212
	v_xor_b32_e32 v230, 32, v211
	v_cmp_lt_i32_e32 vcc, v204, v231
	v_lshlrev_b64 v[212:213], 12, v[196:197]
	s_waitcnt vmcnt(4)
	v_pk_fma_f32 v[126:127], v[126:127], 0.5, v[216:217] op_sel_hi:[1,0,1]
	v_cndmask_b32_e32 v204, v211, v204, vcc
	v_cmp_lt_i32_e32 vcc, v230, v231
	v_pk_fma_f32 v[124:125], v[124:125], 0.5, v[214:215] op_sel_hi:[1,0,1]
	v_pk_fma_f32 v[122:123], v[122:123], 0.5, v[220:221] op_sel_hi:[1,0,1]
	v_pk_fma_f32 v[120:121], v[120:121], 0.5, v[218:219] op_sel_hi:[1,0,1]
	v_pk_fma_f32 v[118:119], v[118:119], 0.5, v[224:225] op_sel_hi:[1,0,1]
	v_pk_fma_f32 v[116:117], v[116:117], 0.5, v[222:223] op_sel_hi:[1,0,1]
	v_pk_fma_f32 v[214:215], v[114:115], 0.5, v[228:229] op_sel_hi:[1,0,1]
	v_pk_fma_f32 v[216:217], v[112:113], 0.5, v[226:227] op_sel_hi:[1,0,1]
	v_cndmask_b32_e32 v232, v211, v230, vcc
	v_lshl_add_u64 v[230:231], s[16:17], 0, v[212:213]
	v_lshlrev_b32_e32 v212, 2, v204
	v_cvt_pk_bf16_f32 v112, v124, v125
	v_cvt_pk_bf16_f32 v113, v126, v127
	v_cvt_pk_bf16_f32 v114, v120, v121
	v_mul_f32_e32 v115, v125, v125
	v_mul_f32_e32 v125, v127, v127
	v_mul_f32_e32 v121, v121, v121
	v_mul_f32_e32 v127, v123, v123
	v_mul_f32_e32 v204, v117, v117
	v_mul_f32_e32 v213, v119, v119
	v_mul_f32_e32 v218, v217, v217
	v_mul_f32_e32 v219, v215, v215
	v_fmac_f32_e32 v115, v124, v124
	v_fmac_f32_e32 v125, v126, v126
	v_fmac_f32_e32 v121, v120, v120
	v_fmac_f32_e32 v127, v122, v122
	v_fmac_f32_e32 v204, v116, v116
	v_fmac_f32_e32 v213, v118, v118
	v_fmac_f32_e32 v218, v216, v216
	v_fmac_f32_e32 v219, v214, v214
	v_add_f32_e32 v115, v115, v125
	v_add_f32_e32 v120, v121, v127
	v_add_f32_e32 v121, v204, v213
	v_add_f32_e32 v124, v218, v219
	v_add_f32_e32 v115, v115, v120
	v_add_f32_e32 v120, v121, v124
	v_add_f32_e32 v120, v115, v120
	ds_bpermute_b32 v121, v212, v120
	v_lshl_add_u64 v[230:231], v[192:193], 1, v[230:231]
	v_cvt_pk_bf16_f32 v115, v122, v123
	global_store_dwordx4 v[230:231], v[112:115], off
	v_cvt_pk_bf16_f32 v116, v116, v117
	v_cvt_pk_bf16_f32 v117, v118, v119
	v_cvt_pk_bf16_f32 v118, v216, v217
	v_cvt_pk_bf16_f32 v119, v214, v215
	global_store_dwordx4 v[230:231], v[116:119], off offset:256
	s_waitcnt lgkmcnt(0)
	v_add_f32_e32 v114, v120, v121
	v_lshlrev_b32_e32 v120, 2, v232
	ds_bpermute_b32 v115, v120, v114
	v_lshl_add_u64 v[112:113], v[196:197], 2, s[12:13]
	s_and_saveexec_b64 s[4:5], s[6:7]
	s_nop 0
	s_waitcnt lgkmcnt(0)
	v_add_f32_e32 v114, v114, v115
	global_atomic_add_f32 v[112:113], v114, off
.LBB0_491:
	s_or_b64 exec, exec, s[4:5]
	v_add_u32_e32 v250, 0x90, v196
	v_ashrrev_i32_e32 v251, 31, v250
	v_lshlrev_b64 v[250:251], 13, v[250:251]
	v_lshl_add_u64 v[250:251], v[194:195], 0, v[250:251]
	global_load_dwordx4 v[214:217], v[250:251], off offset:16
	global_load_dwordx4 v[218:221], v[250:251], off
	global_load_dwordx4 v[222:225], v[250:251], off offset:528
	global_load_dwordx4 v[226:229], v[250:251], off offset:512
	v_pk_fma_f32 v[108:109], v[108:109], 0.5, v[172:173] op_sel_hi:[1,0,1]
	v_pk_fma_f32 v[110:111], v[110:111], 0.5, v[174:175] op_sel_hi:[1,0,1]
	v_pk_fma_f32 v[118:119], v[104:105], 0.5, v[168:169] op_sel_hi:[1,0,1]
	v_cvt_pk_bf16_f32 v104, v108, v109
	v_mul_f32_e32 v109, v109, v109
	v_fmac_f32_e32 v109, v108, v108
	v_mul_f32_e32 v108, v111, v111
	v_pk_fma_f32 v[116:117], v[106:107], 0.5, v[170:171] op_sel_hi:[1,0,1]
	v_fmac_f32_e32 v108, v110, v110
	v_cvt_pk_bf16_f32 v105, v110, v111
	v_add_f32_e32 v108, v109, v108
	v_mul_f32_e32 v109, v119, v119
	v_mul_f32_e32 v110, v117, v117
	v_fmac_f32_e32 v109, v118, v118
	v_fmac_f32_e32 v110, v116, v116
	v_pk_fma_f32 v[102:103], v[102:103], 0.5, v[166:167] op_sel_hi:[1,0,1]
	v_pk_fma_f32 v[100:101], v[100:101], 0.5, v[164:165] op_sel_hi:[1,0,1]
	v_add_f32_e32 v109, v109, v110
	v_pk_fma_f32 v[110:111], v[96:97], 0.5, v[160:161] op_sel_hi:[1,0,1]
	v_mul_f32_e32 v96, v101, v101
	v_mul_f32_e32 v97, v103, v103
	v_cvt_pk_bf16_f32 v106, v118, v119
	v_cvt_pk_bf16_f32 v107, v116, v117
	v_add_f32_e32 v116, v108, v109
	v_pk_fma_f32 v[108:109], v[98:99], 0.5, v[162:163] op_sel_hi:[1,0,1]
	v_fmac_f32_e32 v96, v100, v100
	v_fmac_f32_e32 v97, v102, v102
	v_add_f32_e32 v96, v96, v97
	v_mul_f32_e32 v97, v111, v111
	v_mul_f32_e32 v98, v109, v109
	v_fmac_f32_e32 v97, v110, v110
	v_fmac_f32_e32 v98, v108, v108
	v_add_f32_e32 v97, v97, v98
	v_add_f32_e32 v96, v96, v97
	v_add_f32_e32 v99, v116, v96
	ds_bpermute_b32 v116, v212, v99
	s_waitcnt lgkmcnt(0)
	v_lshlrev_b64 v[114:115], 12, v[202:203]
	v_lshl_add_u64 v[96:97], s[16:17], 0, v[114:115]
	v_lshl_add_u64 v[114:115], v[192:193], 1, v[96:97]
	global_store_dwordx4 v[114:115], v[104:107], off
	v_add_f32_e32 v96, v99, v116
	ds_bpermute_b32 v97, v120, v96
	v_cvt_pk_bf16_f32 v98, v100, v101
	v_cvt_pk_bf16_f32 v99, v102, v103
	v_cvt_pk_bf16_f32 v100, v110, v111
	v_cvt_pk_bf16_f32 v101, v108, v109
	global_store_dwordx4 v[114:115], v[98:101], off offset:256
	s_and_saveexec_b64 s[4:5], s[6:7]
	s_nop 0
	s_waitcnt lgkmcnt(0)
	v_add_f32_e32 v96, v96, v97
	global_atomic_add_f32 v[112:113], v96, off offset:64
.LBB0_493:
	s_or_b64 exec, exec, s[4:5]
	v_add_u32_e32 v250, 0xa0, v196
	v_ashrrev_i32_e32 v251, 31, v250
	v_lshlrev_b64 v[250:251], 13, v[250:251]
	v_lshl_add_u64 v[250:251], v[194:195], 0, v[250:251]
	global_load_dwordx4 v[160:163], v[250:251], off offset:16
	global_load_dwordx4 v[164:167], v[250:251], off
	global_load_dwordx4 v[168:171], v[250:251], off offset:528
	global_load_dwordx4 v[172:175], v[250:251], off offset:512
	v_pk_fma_f32 v[92:93], v[92:93], 0.5, v[156:157] op_sel_hi:[1,0,1]
	v_pk_fma_f32 v[94:95], v[94:95], 0.5, v[158:159] op_sel_hi:[1,0,1]
	v_pk_fma_f32 v[100:101], v[88:89], 0.5, v[152:153] op_sel_hi:[1,0,1]
	v_cvt_pk_bf16_f32 v88, v92, v93
	v_mul_f32_e32 v93, v93, v93
	v_fmac_f32_e32 v93, v92, v92
	v_mul_f32_e32 v92, v95, v95
	v_pk_fma_f32 v[98:99], v[90:91], 0.5, v[154:155] op_sel_hi:[1,0,1]
	v_fmac_f32_e32 v92, v94, v94
	v_cvt_pk_bf16_f32 v89, v94, v95
	v_add_f32_e32 v92, v93, v92
	v_mul_f32_e32 v93, v101, v101
	v_mul_f32_e32 v94, v99, v99
	v_fmac_f32_e32 v93, v100, v100
	v_fmac_f32_e32 v94, v98, v98
	v_pk_fma_f32 v[86:87], v[86:87], 0.5, v[150:151] op_sel_hi:[1,0,1]
	v_pk_fma_f32 v[84:85], v[84:85], 0.5, v[148:149] op_sel_hi:[1,0,1]
	v_add_f32_e32 v93, v93, v94
	v_pk_fma_f32 v[94:95], v[80:81], 0.5, v[144:145] op_sel_hi:[1,0,1]
	v_mul_f32_e32 v80, v85, v85
	v_mul_f32_e32 v81, v87, v87
	v_cvt_pk_bf16_f32 v90, v100, v101
	v_cvt_pk_bf16_f32 v91, v98, v99
	v_add_f32_e32 v98, v92, v93
	v_pk_fma_f32 v[92:93], v[82:83], 0.5, v[146:147] op_sel_hi:[1,0,1]
	v_fmac_f32_e32 v80, v84, v84
	v_fmac_f32_e32 v81, v86, v86
	v_add_f32_e32 v80, v80, v81
	v_mul_f32_e32 v81, v95, v95
	v_mul_f32_e32 v82, v93, v93
	v_fmac_f32_e32 v81, v94, v94
	v_fmac_f32_e32 v82, v92, v92
	v_add_f32_e32 v81, v81, v82
	v_add_f32_e32 v80, v80, v81
	v_add_f32_e32 v83, v98, v80
	ds_bpermute_b32 v98, v212, v83
	s_waitcnt lgkmcnt(0)
	v_lshlrev_b64 v[96:97], 12, v[200:201]
	v_lshl_add_u64 v[80:81], s[16:17], 0, v[96:97]
	v_lshl_add_u64 v[96:97], v[192:193], 1, v[80:81]
	global_store_dwordx4 v[96:97], v[88:91], off
	v_add_f32_e32 v80, v83, v98
	ds_bpermute_b32 v81, v120, v80
	v_cvt_pk_bf16_f32 v82, v84, v85
	v_cvt_pk_bf16_f32 v83, v86, v87
	v_cvt_pk_bf16_f32 v84, v94, v95
	v_cvt_pk_bf16_f32 v85, v92, v93
	global_store_dwordx4 v[96:97], v[82:85], off offset:256
	s_and_saveexec_b64 s[4:5], s[6:7]
	s_nop 0
	s_waitcnt lgkmcnt(0)
	v_add_f32_e32 v80, v80, v81
	global_atomic_add_f32 v[112:113], v80, off offset:128
.LBB0_495:
	s_or_b64 exec, exec, s[4:5]
	v_add_u32_e32 v250, 0xb0, v196
	v_ashrrev_i32_e32 v251, 31, v250
	v_lshlrev_b64 v[250:251], 13, v[250:251]
	v_lshl_add_u64 v[250:251], v[194:195], 0, v[250:251]
	global_load_dwordx4 v[144:147], v[250:251], off offset:16
	global_load_dwordx4 v[148:151], v[250:251], off
	global_load_dwordx4 v[152:155], v[250:251], off offset:528
	global_load_dwordx4 v[156:159], v[250:251], off offset:512
	v_pk_fma_f32 v[76:77], v[76:77], 0.5, v[140:141] op_sel_hi:[1,0,1]
	v_pk_fma_f32 v[78:79], v[78:79], 0.5, v[142:143] op_sel_hi:[1,0,1]
	v_pk_fma_f32 v[84:85], v[72:73], 0.5, v[136:137] op_sel_hi:[1,0,1]
	v_cvt_pk_bf16_f32 v72, v76, v77
	v_mul_f32_e32 v77, v77, v77
	v_fmac_f32_e32 v77, v76, v76
	v_mul_f32_e32 v76, v79, v79
	v_pk_fma_f32 v[82:83], v[74:75], 0.5, v[138:139] op_sel_hi:[1,0,1]
	v_fmac_f32_e32 v76, v78, v78
	v_cvt_pk_bf16_f32 v73, v78, v79
	v_add_f32_e32 v76, v77, v76
	v_mul_f32_e32 v77, v85, v85
	v_mul_f32_e32 v78, v83, v83
	v_fmac_f32_e32 v77, v84, v84
	v_fmac_f32_e32 v78, v82, v82
	v_pk_fma_f32 v[70:71], v[70:71], 0.5, v[134:135] op_sel_hi:[1,0,1]
	v_pk_fma_f32 v[68:69], v[68:69], 0.5, v[132:133] op_sel_hi:[1,0,1]
	v_add_f32_e32 v77, v77, v78
	v_pk_fma_f32 v[78:79], v[64:65], 0.5, v[128:129] op_sel_hi:[1,0,1]
	v_mul_f32_e32 v64, v69, v69
	v_mul_f32_e32 v65, v71, v71
	v_cvt_pk_bf16_f32 v74, v84, v85
	v_cvt_pk_bf16_f32 v75, v82, v83
	v_add_f32_e32 v82, v76, v77
	v_pk_fma_f32 v[76:77], v[66:67], 0.5, v[130:131] op_sel_hi:[1,0,1]
	v_fmac_f32_e32 v64, v68, v68
	v_fmac_f32_e32 v65, v70, v70
	v_add_f32_e32 v64, v64, v65
	v_mul_f32_e32 v65, v79, v79
	v_mul_f32_e32 v66, v77, v77
	v_fmac_f32_e32 v65, v78, v78
	v_fmac_f32_e32 v66, v76, v76
	v_add_f32_e32 v65, v65, v66
	v_add_f32_e32 v64, v64, v65
	v_add_f32_e32 v67, v82, v64
	ds_bpermute_b32 v82, v212, v67
	s_waitcnt lgkmcnt(0)
	v_lshlrev_b64 v[80:81], 12, v[198:199]
	v_lshl_add_u64 v[64:65], s[16:17], 0, v[80:81]
	v_lshl_add_u64 v[80:81], v[192:193], 1, v[64:65]
	global_store_dwordx4 v[80:81], v[72:75], off
	v_add_f32_e32 v64, v67, v82
	ds_bpermute_b32 v65, v120, v64
	v_cvt_pk_bf16_f32 v66, v68, v69
	v_cvt_pk_bf16_f32 v67, v70, v71
	v_cvt_pk_bf16_f32 v68, v78, v79
	v_cvt_pk_bf16_f32 v69, v76, v77
	global_store_dwordx4 v[80:81], v[66:69], off offset:256
	s_and_saveexec_b64 s[4:5], s[6:7]
	s_nop 0
	s_waitcnt lgkmcnt(0)
	v_add_f32_e32 v64, v64, v65
	global_atomic_add_f32 v[112:113], v64, off offset:192
.LBB0_497:
	s_or_b64 exec, exec, s[4:5]
	v_add_u32_e32 v138, 0x80, v196
	v_ashrrev_i32_e32 v139, 31, v138
	s_waitcnt lgkmcnt(0)
	v_lshlrev_b64 v[64:65], 13, v[138:139]
	v_lshl_add_u64 v[64:65], v[194:195], 0, v[64:65]
	s_waitcnt vmcnt(3)
	v_mov_b64_e32 v[122:123], v[234:235]
	v_mov_b64_e32 v[124:125], v[236:237]
	v_mov_b64_e32 v[126:127], v[238:239]
	v_mov_b64_e32 v[128:129], v[240:241]
	v_mov_b64_e32 v[130:131], v[242:243]
	v_mov_b64_e32 v[132:133], v[244:245]
	v_mov_b64_e32 v[134:135], v[246:247]
	v_mov_b64_e32 v[136:137], v[248:249]
	v_add_u32_e32 v118, 0x90, v196
	v_add_u32_e32 v116, 0xa0, v196
	v_add_u32_e32 v114, 0xb0, v196
	v_ashrrev_i32_e32 v119, 31, v118
	v_ashrrev_i32_e32 v117, 31, v116
	v_ashrrev_i32_e32 v115, 31, v114
	v_lshlrev_b64 v[64:65], 13, v[118:119]
	v_lshlrev_b64 v[66:67], 13, v[116:117]
	v_lshlrev_b64 v[68:69], 13, v[114:115]
	v_lshl_add_u64 v[64:65], v[194:195], 0, v[64:65]
	v_lshl_add_u64 v[66:67], v[194:195], 0, v[66:67]
	v_lshl_add_u64 v[68:69], v[194:195], 0, v[68:69]
	v_mov_b64_e32 v[104:105], v[214:215]
	v_mov_b64_e32 v[106:107], v[216:217]
	v_mov_b64_e32 v[108:109], v[218:219]
	v_mov_b64_e32 v[110:111], v[220:221]
	v_mov_b64_e32 v[96:97], v[222:223]
	v_mov_b64_e32 v[98:99], v[224:225]
	v_mov_b64_e32 v[100:101], v[226:227]
	v_mov_b64_e32 v[102:103], v[228:229]
	v_mov_b64_e32 v[88:89], v[160:161]
	v_mov_b64_e32 v[90:91], v[162:163]
	v_mov_b64_e32 v[92:93], v[164:165]
	v_mov_b64_e32 v[94:95], v[166:167]
	v_mov_b64_e32 v[80:81], v[168:169]
	v_mov_b64_e32 v[82:83], v[170:171]
	v_mov_b64_e32 v[84:85], v[172:173]
	v_mov_b64_e32 v[86:87], v[174:175]
	v_mov_b64_e32 v[72:73], v[144:145]
	v_mov_b64_e32 v[74:75], v[146:147]
	v_mov_b64_e32 v[76:77], v[148:149]
	v_mov_b64_e32 v[78:79], v[150:151]
	s_nop 0
	v_mov_b64_e32 v[64:65], v[152:153]
	v_mov_b64_e32 v[66:67], v[154:155]
	s_nop 0
	v_mov_b64_e32 v[68:69], v[156:157]
	v_mov_b64_e32 v[70:71], v[158:159]
	v_lshlrev_b64 v[138:139], 12, v[138:139]
	v_pk_fma_f32 v[62:63], v[62:63], 0.5, v[124:125] op_sel_hi:[1,0,1]
	v_pk_fma_f32 v[60:61], v[60:61], 0.5, v[122:123] op_sel_hi:[1,0,1]
	v_pk_fma_f32 v[58:59], v[58:59], 0.5, v[128:129] op_sel_hi:[1,0,1]
	v_pk_fma_f32 v[56:57], v[56:57], 0.5, v[126:127] op_sel_hi:[1,0,1]
	v_pk_fma_f32 v[54:55], v[54:55], 0.5, v[132:133] op_sel_hi:[1,0,1]
	v_pk_fma_f32 v[52:53], v[52:53], 0.5, v[130:131] op_sel_hi:[1,0,1]
	v_pk_fma_f32 v[122:123], v[50:51], 0.5, v[136:137] op_sel_hi:[1,0,1]
	v_pk_fma_f32 v[124:125], v[48:49], 0.5, v[134:135] op_sel_hi:[1,0,1]
	v_cvt_pk_bf16_f32 v48, v60, v61
	v_cvt_pk_bf16_f32 v49, v62, v63
	v_cvt_pk_bf16_f32 v50, v56, v57
	v_cvt_pk_bf16_f32 v51, v58, v59
	v_mul_f32_e32 v61, v61, v61
	v_mul_f32_e32 v63, v63, v63
	v_mul_f32_e32 v57, v57, v57
	v_mul_f32_e32 v59, v59, v59
	v_mul_f32_e32 v121, v53, v53
	v_mul_f32_e32 v126, v55, v55
	v_mul_f32_e32 v127, v125, v125
	v_mul_f32_e32 v128, v123, v123
	v_fmac_f32_e32 v61, v60, v60
	v_fmac_f32_e32 v63, v62, v62
	v_fmac_f32_e32 v57, v56, v56
	v_fmac_f32_e32 v59, v58, v58
	v_fmac_f32_e32 v121, v52, v52
	v_fmac_f32_e32 v126, v54, v54
	v_fmac_f32_e32 v127, v124, v124
	v_fmac_f32_e32 v128, v122, v122
	v_add_f32_e32 v56, v61, v63
	v_add_f32_e32 v57, v57, v59
	v_add_f32_e32 v58, v121, v126
	v_add_f32_e32 v59, v127, v128
	v_add_f32_e32 v56, v56, v57
	v_add_f32_e32 v57, v58, v59
	v_add_f32_e32 v58, v56, v57
	ds_bpermute_b32 v59, v212, v58
	v_lshl_add_u64 v[56:57], s[16:17], 0, v[138:139]
	v_lshl_add_u64 v[56:57], v[192:193], 1, v[56:57]
	global_store_dwordx4 v[56:57], v[48:51], off
	s_waitcnt lgkmcnt(0)
	s_nop 0
	v_add_f32_e32 v48, v58, v59
	ds_bpermute_b32 v49, v120, v48
	v_cvt_pk_bf16_f32 v50, v52, v53
	v_cvt_pk_bf16_f32 v51, v54, v55
	v_cvt_pk_bf16_f32 v52, v124, v125
	v_cvt_pk_bf16_f32 v53, v122, v123
	global_store_dwordx4 v[56:57], v[50:53], off offset:256
	s_and_saveexec_b64 s[4:5], s[6:7]
	s_cbranch_execz .LBB0_499
	s_waitcnt lgkmcnt(0)
	v_add_f32_e32 v48, v48, v49
	global_atomic_add_f32 v[112:113], v48, off offset:512
